# attention mask-free loop: rotated back edge (next step's stage addresses before the barrier, one taken branch back into the wave's own body)
# speedup vs baseline: 1.0048x; 1.0048x over previous
.LBB0_116:
	s_add_i32 s97, s97, 64
	s_cmp_eq_u32 s99, s6
	s_waitcnt lgkmcnt(0)
	s_barrier
	s_cbranch_scc1 .LBB0_120
	s_mov_b32 s42, s6
	s_branch .LBB0_107
.Lnd_107:
	s_and_b32 s33, s42, 1
	s_mul_i32 s6, s33, 0x9000
	v_add_u32_e32 v199, s6, v187
	v_add_u32_e32 v198, s6, v188
	s_mov_b64 s[54:55], exec
	v_readfirstlane_b32 s4, v186
	s_bitcmp1_b32 s4, 8
	s_cbranch_scc1 .Lab_B

.Lq_endA:
	s_add_i32 s97, s97, 64
	s_mov_b32 s42, s6
	s_and_b32 s33, s42, 1
	s_mul_i32 s6, s33, 0x9000
	v_add_u32_e32 v199, s6, v187
	v_add_u32_e32 v198, s6, v188
	s_cmp_lt_u32 s42, s98
	s_waitcnt lgkmcnt(0)
	s_barrier
	s_cbranch_scc1 .Lq_A
	s_branch .LBB0_107
